# P4 branch-GEMM unit order remapped: 4 pn-units of one A tile on same XCD, late-needed token tiles first
# speedup vs baseline: 1.0141x; 1.0141x over previous
; #define LAS __attribute__((address_space(3)))
; #define FRESH_IDS() int tid_ = wave_s * 64 + fresh_lane(); const int tid = tid_, lane = tid & 63, wave = __builtin_amdgcn_readfirstlane(tid >> 6), gw = vcu * NWAVES + wave; (void)gw; (void)lane; (void)tid
; #define GSYNC() do { xcd_barrier(xbar, wave_s); xcd_barrier(xbar, wave_s); xcd_barrier(xbar, wave_s); } while (0)
; #define GSYNC() xcd_barrier(xbar, wave_s)
;     DI bool next(int i, Unit& u) const {
;         const int L = i * G + c; if (L >= 2048) return false;
;         const int br = L >> 9, rem = L & 511; u.pm = br * 128 + (rem >> 2); u.pn = br * 4 + (rem & 3); return true;
; __global__ void __launch_bounds__(NWAVES * 64 LB2) fwd_kernel(Params P) {
;     ...
;     for (int l = 0; l < DEPTH; ++l) {
;         const float* xin = (l == 0) ? P.in[0] : (const float*)P.out;
;         unsigned char* wl = P.ws + WS_W + (size_t)l * WL_STRIDE;
;         if (l > 0) { FRESH_IDS(); rms_phase(xin, P.in[1] + (size_t)l * DM, XN, gw, NGW, lane); GSYNC(); }
;         {
;             pg8::Gemm g{XN, (const bf16_t*)(wl + WL_IN), TOK, NIN, DM}; pg8::StaticOrder S; S.init(TOK, NIN, G, bx);
;             pg8::EpiStore E{HB, NIN};
;             if (((PH_MASK & 8u) != 0u) & ((GEMM_SEL & 1u) != 0u)) pg8::gemm_phase<pg8::EpiStore, pg8::StaticOrder, true, true>(lds, g, S, E, wave_s);
;     ...
;             __syncthreads();
;             if (((PH_MASK & 8u) != 0u) & ((GEMM_SEL & 1u) != 0u)) pg8::gemm_phase<pg8::EpiStore, pg8::StaticOrder, true, true>(lds, g, S, E, wave_s);
;     ...
;         }
;         GSYNC();
;         if (PH_MASK & 2u) { FRESH_IDS(); prep_phase(P, l, lds, G, bx, gw, NGW, wave, lane); }
;         GSYNC();
;         if (PH_MASK & 4u) { attn_phase(P, l, (LAS char*)lds, G, bx, wave_s); }
;     ...
;         grid.sync(); attn_phase(P, l, (LAS char*)lds, G, bx, wave_s);
;     ...
;         GSYNC();
;         {
;             pg8::Gemm g{OB, (const bf16_t*)(wl + WL_B), 4 * TOK, 4096, 256}; pg8::DiagOrder S{G, bx};
;             pg8::EpiT E{TB};
;             if (((PH_MASK & 8u) != 0u) & ((GEMM_SEL & 2u) != 0u)) pg8::gemm_phase<pg8::EpiT, pg8::DiagOrder, true, true>(lds, g, S, E, wave_s);
.LBB0_184:
	s_add_u32 s6, s46, 0xc800000
	s_addc_u32 s7, s47, 0
	s_add_u32 s8, s46, 0x8800000
	s_addc_u32 s9, s47, 0
	s_waitcnt lgkmcnt(0)
	s_barrier
	s_load_dwordx4 s[88:91], s[0:1], 0xa8
	s_add_u32 s4, s46, 0x14800000
	s_addc_u32 s5, s47, 0
	v_writelane_b32 v253, s4, 4
	s_load_dwordx4 s[12:15], s[0:1], 0x0
	s_load_dwordx16 s[48:63], s[0:1], 0x18
	v_writelane_b32 v253, s5, 5
	s_lshr_b32 s4, s36, 6
	s_waitcnt lgkmcnt(0)
	s_add_u32 s5, s90, 0x200000
	v_writelane_b32 v253, s5, 6
	s_addc_u32 s5, s91, 0
	v_writelane_b32 v253, s5, 7
	s_add_u32 s10, s14, 0x1000
	v_writelane_b32 v253, s12, 8
	s_addc_u32 s11, s15, 0
	s_mul_i32 s5, s97, s96
	v_writelane_b32 v253, s13, 9
	v_writelane_b32 v253, s14, 10
	v_writelane_b32 v253, s15, 11
	v_writelane_b32 v253, s10, 12
	s_mul_i32 s5, s5, s38
	s_mov_b32 s23, 0
	v_writelane_b32 v253, s11, 13
	s_add_u32 s10, s46, 0x200
	v_writelane_b32 v253, s5, 14
	s_addc_u32 s11, s47, 0
	v_writelane_b32 v253, s10, 15
	v_mov_b32_e32 v169, 0
	v_mov_b32_e32 v185, 0x358637bd
	v_writelane_b32 v253, s11, 16
	s_add_u32 s10, s46, 0x1000
	s_addc_u32 s11, s47, 0
	v_writelane_b32 v253, s10, 17
	v_mov_b32_e32 v194, 0x260
	v_mov_b32_e32 v195, 1
	v_writelane_b32 v253, s11, 18
	s_add_u32 s10, s46, 0x1100
	s_addc_u32 s11, s47, 0
	v_writelane_b32 v253, s10, 19
	v_mov_b32_e32 v196, 0x80
	v_mov_b32_e32 v197, 0x100
	v_writelane_b32 v253, s11, 20
	s_add_u32 s10, s46, 0x1200
	s_addc_u32 s11, s47, 0
	v_writelane_b32 v253, s10, 21
	v_mov_b32_e32 v198, 0x200
	v_mov_b32_e32 v199, 0x400
	v_writelane_b32 v253, s11, 22
	s_add_u32 s10, s46, 0x1300
	s_addc_u32 s11, s47, 0
	v_writelane_b32 v253, s10, 23
	s_cmp_eq_u32 s37, 15
	v_mov_b32_e32 v200, 0x800
	v_writelane_b32 v253, s11, 24
	s_cselect_b64 s[10:11], -1, 0
	v_writelane_b32 v253, s10, 25
	s_cmp_eq_u32 s37, 14
	v_mov_b32_e32 v201, 0x1000
	v_writelane_b32 v253, s11, 26
	s_cselect_b64 s[10:11], -1, 0
	v_writelane_b32 v253, s10, 27
	s_cmp_eq_u32 s37, 13
	v_mov_b32_e32 v202, 0x2000
	v_writelane_b32 v253, s11, 28
	s_cselect_b64 s[10:11], -1, 0
	v_writelane_b32 v253, s10, 29
	s_cmp_eq_u32 s37, 12
	v_mov_b32_e32 v203, 0x4000
	v_writelane_b32 v253, s11, 30
	s_cselect_b64 s[10:11], -1, 0
	v_writelane_b32 v253, s10, 31
	s_cmp_eq_u32 s37, 11
	v_mov_b32_e32 v204, 0x8000
	v_writelane_b32 v253, s11, 32
	s_cselect_b64 s[10:11], -1, 0
	v_writelane_b32 v253, s10, 33
	s_cmp_eq_u32 s37, 10
	v_mov_b32_e32 v170, 0x3f4ccccd
	v_writelane_b32 v253, s11, 34
	s_cselect_b64 s[10:11], -1, 0
	v_writelane_b32 v253, s10, 35
	s_cmp_eq_u32 s37, 9
	v_mov_b32_e32 v252, 0x42800000
	v_writelane_b32 v253, s11, 36
	s_cselect_b64 s[10:11], -1, 0
	v_writelane_b32 v253, s10, 37
	s_cmp_eq_u32 s37, 8
	v_not_b32_e32 v205, 63
	v_writelane_b32 v253, s11, 38
	s_cselect_b64 s[10:11], -1, 0
	v_writelane_b32 v253, s10, 39
	s_cmp_eq_u32 s37, 7
	v_mov_b32_e32 v208, 0xf149f2ca
	v_writelane_b32 v253, s11, 40
	s_cselect_b64 s[10:11], -1, 0
	v_writelane_b32 v253, s10, 41
	s_cmp_eq_u32 s37, 6
	v_mov_b32_e32 v209, 0x7f61b1e6
	v_writelane_b32 v253, s11, 42
	s_cselect_b64 s[10:11], -1, 0
	v_writelane_b32 v253, s10, 43
	s_cmp_eq_u32 s37, 5
	v_mov_b32_e32 v210, 0x7f800000
	v_writelane_b32 v253, s11, 44
	s_cselect_b64 s[10:11], -1, 0
	v_writelane_b32 v253, s10, 45
	s_cmp_eq_u32 s37, 4
	v_mov_b32_e32 v211, 0x41b17218
	v_writelane_b32 v253, s11, 46
	s_cselect_b64 s[10:11], -1, 0
	v_writelane_b32 v253, s10, 47
	s_cmp_eq_u32 s37, 3
	v_mov_b64_e32 v[174:175], 0x7ff
	v_writelane_b32 v253, s11, 48
	s_cselect_b64 s[10:11], -1, 0
	v_writelane_b32 v253, s10, 49
	s_cmp_eq_u32 s37, 2
	v_mov_b64_e32 v[176:177], 0x200
	v_writelane_b32 v253, s11, 50
	s_cselect_b64 s[10:11], -1, 0
	v_writelane_b32 v253, s10, 51
	s_cmp_eq_u32 s37, 1
	v_mov_b64_e32 v[178:179], 0x1ff
	v_writelane_b32 v253, s11, 52
	s_cselect_b64 s[10:11], -1, 0
	v_writelane_b32 v253, s10, 53
	s_cmp_eq_u32 s37, 0
	v_mov_b64_e32 v[180:181], 0xb00
	v_writelane_b32 v253, s11, 54
	s_cselect_b64 s[10:11], -1, 0
	s_lshl_b32 s5, s37, 8
	v_writelane_b32 v253, s10, 55
	s_add_u32 s5, s46, s5
	v_mov_b64_e32 v[182:183], 0xaff
	v_writelane_b32 v253, s11, 56
	s_addc_u32 s10, s47, 0
	s_add_u32 s12, s5, 0x1400
	s_addc_u32 s13, s10, 0
	v_writelane_b32 v253, s12, 57
	s_mov_b32 s83, 0xf800000
	s_movk_i32 s82, 0x1800
	v_writelane_b32 v253, s13, 58
	s_add_u32 s12, s5, 0x2400
	s_addc_u32 s13, s10, 0
	v_writelane_b32 v253, s12, 59
	s_add_u32 s10, s46, 0x3400
	s_addc_u32 s11, s47, 0
	v_writelane_b32 v253, s13, 60
	v_writelane_b32 v253, s10, 61
	s_mov_b32 s30, 0x3f317217
	s_movk_i32 s31, 0x1600
	v_writelane_b32 v253, s11, 62
	s_add_u32 s10, s46, 0x3500
	s_addc_u32 s11, s47, 0
	v_writelane_b32 v253, s10, 63
	s_cmpk_lt_i32 s2, 0x600
	s_mov_b64 s[34:35], 0
	v_writelane_b32 v254, s11, 0
	s_cselect_b64 s[10:11], -1, 0
	s_ashr_i32 s95, s2, 31
	s_lshr_b32 s5, s95, 29
	s_add_i32 s5, s2, s5
	s_ashr_i32 s12, s5, 3
	s_and_b32 s5, s5, -8
	s_sub_i32 s5, s2, s5
	s_ashr_i32 s73, s96, 31
	v_writelane_b32 v254, s10, 1
	s_cmpk_lt_i32 s2, 0x80
	s_mov_b32 s94, 0x3e38aa3b
	v_writelane_b32 v254, s11, 2
	s_cselect_b64 s[10:11], -1, 0
	s_add_u32 s28, s90, 0xc800000
	v_writelane_b32 v254, s10, 3
	s_addc_u32 s29, s91, 0
	s_mov_b32 s72, 0x3e8293ee
	v_writelane_b32 v254, s11, 4
	s_add_u32 s10, s90, 0x100000
	v_writelane_b32 v254, s10, 5
	s_addc_u32 s10, s91, 0
	v_writelane_b32 v254, s10, 6
	s_add_u32 s10, s90, 0x4700000
	s_addc_u32 s11, s91, 0
	v_writelane_b32 v254, s10, 7
	s_mov_b32 s74, s23
	s_nop 0
	v_writelane_b32 v254, s11, 8
	s_lshr_b32 s11, s36, 3
	s_and_b32 s19, s11, 0x1fffffe0
	s_lshl_b32 s11, s19, 3
	s_add_i32 s11, s11, 0
	s_add_i32 s11, s11, 0x22000
	v_writelane_b32 v254, s11, 9
	s_lshl_b32 s11, s4, 13
	s_not_b32 s10, s2
	s_add_i32 s11, s11, 0
	s_add_i32 s78, s96, s10
	s_bfe_u32 s10, s36, 0x20006
	s_add_i32 s11, s11, 0x12000
	v_writelane_b32 v254, s11, 10
	s_lshl_b32 s11, s10, 6
	s_add_u32 s13, s90, 0x40000
	v_writelane_b32 v254, s13, 11
	s_addc_u32 s13, s91, 0
	v_writelane_b32 v254, s13, 12
	s_add_u32 s13, s90, 0x80000
	v_writelane_b32 v254, s13, 13
	s_addc_u32 s13, s91, 0
	s_add_u32 s84, s90, 0x8800000
	v_writelane_b32 v254, s13, 14
	s_addc_u32 s85, s91, 0
	s_lshl_b32 s13, s10, 7
	s_add_u32 s14, s84, s13
	s_addc_u32 s15, s85, 0
	s_lshl_b32 s92, s4, 5
	s_mulk_i32 s4, 0x2400
	v_writelane_b32 v254, s14, 15
	s_add_i32 s4, s4, 0
	s_cmpk_lt_i32 s2, 0x800
	v_writelane_b32 v254, s15, 16
	v_writelane_b32 v254, s4, 17
	s_cselect_b64 s[14:15], -1, 0
	v_writelane_b32 v254, s14, 18
	s_cmp_lg_u32 s96, 0x100
	v_writelane_b32 v254, s15, 19
	s_cbranch_scc1 .Lp4_first_orig
	s_lshr_b32 s14, s2, 5
	s_lshl_b32 s14, s14, 4
	s_and_b32 s13, s2, 7
	s_or_b32 s14, s14, s13
	s_or_b32 s14, s14, 8
	s_bfe_u32 s4, s2, 0x20003
	s_branch .Lp4_first_done
;     __host__ __device__ bool next(int i, Unit& u) const {
;         const long L = (long)i * G + c; if (L >= nwg) return false;
;         int wgid = (int)L; { const int q = nwg / NXCD, r = nwg % NXCD, xcd = wgid % NXCD, off = wgid / NXCD; wgid = (xcd < r ? xcd * (q + 1) : r * (q + 1) + (xcd - r) * q) + off; }
;         const int nig = WGM * nN, gid = wgid / nig, fm = gid * WGM, gsz = (nM - fm) < WGM ? (nM - fm) : WGM;
;         u.pm = fm + ((wgid % nig) % gsz); u.pn = (wgid % nig) / gsz; return true;
;     }
;     DI bool next(int i, Unit& u) const {
;         const int L = i * G + c; if (L >= 2048) return false;
;         const int br = L >> 9, rem = L & 511; u.pm = br * 128 + (rem >> 2); u.pn = br * 4 + (rem & 3); return true;
.Lp4_first_orig:
	s_ashr_i32 s4, s2, 9
	s_lshl_b32 s13, s4, 7
	s_bfe_u32 s14, s2, 0x70002
	s_or_b32 s14, s13, s14
	s_lshl_b32 s4, s4, 2
	s_and_b32 s13, s2, 3
	s_or_b32 s4, s4, s13
.Lp4_first_done:
	v_writelane_b32 v254, s14, 20
	s_ashr_i32 s13, s14, 31
	v_writelane_b32 v254, s13, 21
	v_writelane_b32 v254, s4, 22
	s_ashr_i32 s4, s4, 31
	v_writelane_b32 v254, s4, 23
	s_lshl_b32 s4, s5, 8
	s_cmpk_lt_i32 s2, 0x200
	s_cselect_b64 s[14:15], -1, 0
	s_lshl_b32 s13, s5, 6
	v_writelane_b32 v254, s14, 24
	s_cmpk_lt_i32 s2, 0xb00
	s_nop 0
	v_writelane_b32 v254, s15, 25
	s_cselect_b64 s[14:15], -1, 0
	v_writelane_b32 v254, s14, 26
	s_cmp_lt_i32 s5, 0
	s_nop 0
	v_writelane_b32 v254, s15, 27
	s_mul_i32 s14, s5, 0x101
	s_cselect_b32 s4, s14, s4
	s_mul_i32 s14, s5, 0x41
	s_cselect_b32 s13, s14, s13
	s_movk_i32 s14, 0xc1
	s_cselect_b32 s14, s14, 0xc0
	s_mul_i32 s14, s5, s14
	s_movk_i32 s15, 0x161
	s_cselect_b32 s15, s15, 0x160
	s_add_i32 s14, s14, s12
	s_mul_hi_i32 s16, s14, 0x2aaaaaab
	s_lshr_b32 s17, s16, 31
	s_ashr_i32 s16, s16, 4
	s_add_i32 s16, s16, s17
	s_mul_i32 s17, s16, 0x60
	s_sub_i32 s14, s14, s17
	s_bfe_i32 s17, s14, 0x80000
	s_bfe_u32 s17, s17, 0x3000c
	s_add_i32 s17, s14, s17
	s_and_b32 s18, s17, 0xf8
	s_sub_i32 s14, s14, s18
	s_lshl_b32 s16, s16, 3
	s_sext_i32_i8 s14, s14
	s_add_i32 s4, s4, s12
	s_add_i32 s20, s16, s14
	s_ashr_i32 s14, s4, 31
	s_lshr_b32 s14, s14, 25
	s_add_i32 s14, s4, s14
	s_and_b32 s16, s14, 0xff80
	s_sub_i32 s4, s4, s16
	s_bfe_i32 s16, s4, 0x80000
	s_bfe_u32 s16, s16, 0x3000c
	s_add_i32 s16, s4, s16
	s_and_b32 s18, s16, 0xf8
	s_sub_i32 s4, s4, s18
	s_ashr_i32 s14, s14, 7
	s_lshl_b32 s14, s14, 3
	s_sext_i32_i8 s4, s4
	s_add_i32 s21, s14, s4
	s_add_i32 s4, s13, s12
	s_ashr_i32 s13, s4, 31
	s_lshr_b32 s13, s13, 27
	s_add_i32 s13, s4, s13
	s_and_b32 s14, s13, 0xffe0
	s_sub_i32 s4, s4, s14
	s_bfe_i32 s14, s4, 0x80000
	s_bfe_u32 s14, s14, 0x3000c
	s_add_i32 s14, s4, s14
	s_and_b32 s18, s14, 0xf8
	s_sub_i32 s4, s4, s18
	s_ashr_i32 s13, s13, 5
	s_lshl_b32 s13, s13, 3
	s_sext_i32_i8 s4, s4
	s_add_i32 s18, s13, s4
	s_mul_i32 s4, s5, s15
	s_add_i32 s4, s4, s12
	s_mul_hi_i32 s5, s4, 0x2e8ba2e9
	s_lshr_b32 s12, s5, 31
	s_ashr_i32 s5, s5, 5
	s_add_i32 s5, s5, s12
	s_mul_i32 s12, s5, 0xb0
	s_sub_i32 s4, s4, s12
	s_bfe_u32 s12, s4, 0x3001c
	s_add_i32 s12, s4, s12
	s_and_b32 s13, s12, 0xfff8
	s_sub_i32 s4, s4, s13
	s_lshl_b32 s5, s5, 3
	s_sext_i32_i16 s4, s4
	s_add_i32 s13, s5, s4
	s_bfe_i32 s4, s17, 0x80000
	s_sext_i32_i16 s4, s4
	s_ashr_i32 s5, s4, 3
	s_lshr_b32 s4, s4, 3
	v_writelane_b32 v254, s5, 28
	s_bfe_i64 s[4:5], s[4:5], 0x100000
	v_writelane_b32 v254, s4, 29
	s_lshl_b32 s10, s10, 1
	s_mov_b32 s15, 0xf149f2ca
	v_writelane_b32 v254, s5, 30
	s_bfe_i32 s4, s16, 0x80000
	s_sext_i32_i16 s4, s4
	s_ashr_i32 s5, s4, 3
	s_lshr_b32 s4, s4, 3
	v_writelane_b32 v254, s5, 31
	s_bfe_i64 s[4:5], s[4:5], 0x100000
	v_writelane_b32 v254, s4, 32
	s_mov_b32 s16, 0xefa18f08
	s_mov_b32 s17, 0xbfb8aa3b
	v_writelane_b32 v254, s5, 33
	s_bfe_i32 s4, s14, 0x80000
	s_sext_i32_i16 s4, s4
	s_ashr_i32 s5, s4, 3
	s_lshr_b32 s4, s4, 3
	v_writelane_b32 v254, s5, 34
	s_bfe_i64 s[4:5], s[4:5], 0x100000
	v_writelane_b32 v254, s4, 35
	s_movk_i32 s14, 0x1000
	s_nop 0
	v_writelane_b32 v254, s5, 36
	s_sext_i32_i16 s4, s12
	s_ashr_i32 s5, s4, 3
	s_lshr_b32 s4, s4, 3
	v_writelane_b32 v254, s5, 37
	s_bfe_i64 s[4:5], s[4:5], 0x100000
	v_writelane_b32 v254, s4, 38
	s_ashr_i32 s12, s20, 31
	s_nop 0
	v_writelane_b32 v254, s5, 39
	v_writelane_b32 v254, s20, 40
	v_writelane_b32 v254, s12, 41
	v_writelane_b32 v254, s21, 42
	s_ashr_i32 s12, s21, 31
	v_writelane_b32 v254, s12, 43
	v_writelane_b32 v254, s18, 44
	s_ashr_i32 s12, s18, 31
	v_writelane_b32 v254, s12, 45
	v_writelane_b32 v254, s13, 46
	s_ashr_i32 s12, s13, 31
	v_writelane_b32 v254, s12, 47
	s_lshl_b32 s12, s2, 4
	v_writelane_b32 v254, s12, 48
	s_lshl_b32 s12, s96, 4
	v_writelane_b32 v254, s12, 49
	v_writelane_b32 v254, s19, 50
	s_add_i32 s12, s11, s19
	v_writelane_b32 v254, s12, 51
	s_add_i32 s12, 0, 0x23fc0
	v_writelane_b32 v254, s12, 52
	s_add_i32 s12, 0, 0x23fc4
	v_writelane_b32 v254, s12, 53
	s_lshl_b32 s12, s11, 1
	v_writelane_b32 v254, s12, 54
	s_mov_b32 s4, 0x6dc9c883
	s_mov_b32 s5, 0x3fc45f30
	v_writelane_b32 v254, s13, 55
	v_writelane_b32 v254, s10, 56
	s_movk_i32 s18, 0xc00
	s_mov_b32 s19, 0x7f800000
	v_writelane_b32 v254, s11, 57
	s_load_dwordx2 s[10:11], s[0:1], 0x58
	s_mov_b32 s20, 0x3e000000
	s_mov_b32 s21, 0x800000
	s_mov_b64 s[12:13], 0x80
	s_waitcnt lgkmcnt(0)
	v_writelane_b32 v254, s10, 58
	s_nop 1
	v_writelane_b32 v254, s11, 59
	s_load_dwordx2 s[10:11], s[0:1], 0x70
	s_waitcnt lgkmcnt(0)
	v_writelane_b32 v254, s10, 60
	s_nop 1
	v_writelane_b32 v254, s11, 61
	s_load_dwordx2 s[10:11], s[0:1], 0x88
	s_waitcnt lgkmcnt(0)
	v_writelane_b32 v254, s10, 62
	s_nop 1
	v_writelane_b32 v254, s11, 63
	s_mov_b64 s[10:11], -1
	v_writelane_b32 v255, s10, 0
	s_nop 1
	v_writelane_b32 v255, s11, 1
	v_writelane_b32 v255, s48, 2
	s_nop 1
	v_writelane_b32 v255, s49, 3
	v_writelane_b32 v255, s50, 4
	v_writelane_b32 v255, s51, 5
	v_writelane_b32 v255, s52, 6
	v_writelane_b32 v255, s53, 7
	v_writelane_b32 v255, s54, 8
	v_writelane_b32 v255, s55, 9
	v_writelane_b32 v255, s56, 10
	v_writelane_b32 v255, s57, 11
	v_writelane_b32 v255, s58, 12
	v_writelane_b32 v255, s59, 13
	v_writelane_b32 v255, s60, 14
	v_writelane_b32 v255, s61, 15
	v_writelane_b32 v255, s62, 16
	v_writelane_b32 v255, s63, 17
	v_writelane_b32 v255, s79, 18
	s_branch .LBB0_189

; template <class Epi, class Sched, bool ALIGN_EPI = false, bool SP2 = false>
; __device__ __forceinline__ void gemm_phase(PG8_LAS unsigned char* lds, const Gemm g, const Sched& S, const Epi& E, const int wave_s) {
;     ...
;         const bool has_next = S.next(ui + 1, nxt);
;         const char* nA = has_next ? (const char*)g.A + (size_t)nxt.pm * tstep : cA; const char* nB = has_next ? (const char*)g.Bt + (size_t)nxt.pn * tstep : cB;
;     DI bool next(int i, Unit& u) const {
;         const int L = i * G + c; if (L >= 2048) return false;
;         const int br = L >> 9, rem = L & 511; u.pm = br * 128 + (rem >> 2); u.pn = br * 4 + (rem & 3); return true;
.LBB0_1002:
	s_add_i32 s61, s61, 1
	s_mul_i32 s26, s61, s96
	s_add_i32 s26, s26, s2
	s_cmpk_lt_i32 s26, 0x800
	s_cselect_b64 s[48:49], -1, 0
	s_cmpk_gt_i32 s26, 0x7ff
	s_cbranch_scc1 .LBB0_1004
	s_cmp_lg_u32 s96, 0x100
	s_cbranch_scc1 .Lp4_loop_orig
	s_and_b32 s36, s61, 3
	s_lshl_b32 s37, s36, 7
	s_lshr_b32 s50, s2, 5
	s_lshl_b32 s50, s50, 4
	s_and_b32 s26, s2, 7
	s_or_b32 s50, s50, s26
	s_lshr_b32 s26, s61, 2
	s_xor_b32 s26, s26, 1
	s_lshl_b32 s26, s26, 3
	s_or_b32 s50, s50, s26
	s_lshl_b32 s36, s36, 2
	s_bfe_u32 s26, s2, 0x20003
	s_or_b32 s62, s37, s50
	s_or_b32 s63, s36, s26
	s_branch .Lp4_loop_done
.Lp4_loop_orig:
	s_ashr_i32 s36, s26, 9
	s_lshl_b32 s37, s36, 7
	s_bfe_u32 s50, s26, 0x70002
	s_lshl_b32 s36, s36, 2
	s_and_b32 s26, s26, 3
	s_or_b32 s62, s37, s50
	s_or_b32 s63, s36, s26
.Lp4_loop_done:
.LBB0_1004:
	v_cndmask_b32_e64 v0, 0, 1, s[48:49]
	v_cmp_ne_u32_e64 s[36:37], 1, v0
	s_andn2_b64 vcc, exec, s[48:49]
	s_mov_b64 s[48:49], s[52:53]
	s_cbranch_vccnz .LBB0_1006
	s_ashr_i32 s26, s62, 31
	s_mul_hi_u32 s48, s38, s62
	s_mul_i32 s26, s38, s26
	s_add_i32 s26, s48, s26
	s_mul_i32 s48, s39, s62
	s_add_i32 s26, s26, s48
	s_mul_i32 s48, s38, s62
	s_add_u32 s48, s8, s48
	s_addc_u32 s49, s9, s26
